# pp_v31 + seams: two staggered sc1 polls in flight per poll-loop iteration (sampling the top counter about twice as often)
# baseline (speedup 1.0000x reference)
.Lfs0_loop:
	global_load_dword v2, v1, s[6:7] sc1
	s_add_u32 s11, s11, 1
	s_sleep 6
	global_load_dword v3, v1, s[6:7] sc1
	s_waitcnt vmcnt(1)
	v_readfirstlane_b32 s12, v2
	s_cmp_ge_u32 s12, s10
	s_cbranch_scc1 .Lfs0_done
	s_waitcnt vmcnt(0)
	v_readfirstlane_b32 s12, v3
	s_cmp_ge_u32 s12, s10
	s_cbranch_scc1 .Lfs0_done
	s_cmp_lt_u32 s11, 0x100000
	s_cbranch_scc1 .Lfs0_loop
